# P11/P14 GEMM tile loops: accumulators zeroed with v_mov_b64 pairs (compiler mid-run vmcnt(0) kept in place)
# baseline (speedup 1.0000x reference)
;     __device__ bool next(int i, Unit& u) const { if (!so.next(i, u)) return false; u.ks = u.pn >= 16 ? 1 : 0; return true; }
; template <class Epi, class Order>
; __device__ __forceinline__ void gemm_phase(LAS unsigned char* lds, const Gemm g, const Order& S, const Epi& E) {
;     ...
;         const bool has_next = S.next(ui + 1, nxt);
;         const char* nA = has_next ? (const char*)g.A + (size_t)nxt.pm * tstep + (size_t)nxt.ks * sstep : cA; const char* nB = has_next ? (const char*)g.Bt + (size_t)nxt.pn * tstep + (size_t)nxt.ks * sstep : cB;
;     ...
;         if (!has_next) break;
; #pragma unroll
;         for (int a = 0; a < 2; ++a)
; #pragma unroll
;             for (int b = 0; b < 2; ++b)
; #pragma unroll
;                 for (int m = 0; m < 4; ++m)
; #pragma unroll
;                     for (int n = 0; n < 2; ++n) acc[a][b][m][n] = (f32x4){0.f, 0.f, 0.f, 0.f};
;         cur = nxt; cA = nA; cB = nB; ++ui;
.LBB0_1001:
	s_ashr_i32 s21, s20, 31
	v_cmp_lt_i64_e32 vcc, s[22:23], v[190:191]
	s_lshl_b64 s[22:23], s[20:21], 20
	s_add_u32 s22, s64, s22
	s_addc_u32 s23, s65, s23
	s_and_b64 s[24:25], vcc, exec
	s_cselect_b32 s21, s23, s45
	s_cselect_b32 s43, s22, s44
	s_ashr_i32 s19, s18, 31
	s_lshl_b64 s[24:25], s[18:19], 20
	s_add_u32 s36, s31, s24
	s_addc_u32 s37, s35, s25
	s_and_b64 s[24:25], vcc, exec
	s_cselect_b32 s19, s37, s47
	s_cselect_b32 s77, s36, s46
	s_add_u32 s44, s44, 0x80080
	s_addc_u32 s45, s45, 0
	s_add_u32 s78, s46, 0x100
	v_mov_b64_e32 v[0:1], 0
	v_mov_b64_e32 v[2:3], 0
	v_mov_b64_e32 v[4:5], 0
	v_mov_b64_e32 v[6:7], 0
	v_mov_b64_e32 v[8:9], 0
	v_mov_b64_e32 v[10:11], 0
	v_mov_b64_e32 v[12:13], 0
	v_mov_b64_e32 v[14:15], 0
	v_mov_b64_e32 v[24:25], 0
	v_mov_b64_e32 v[26:27], 0
	v_mov_b64_e32 v[28:29], 0
	v_mov_b64_e32 v[30:31], 0
	v_mov_b64_e32 v[36:37], 0
	v_mov_b64_e32 v[38:39], 0
	v_mov_b64_e32 v[44:45], 0
	v_mov_b64_e32 v[46:47], 0
	s_addc_u32 s79, s47, 0
	s_mov_b32 s80, -2
	s_waitcnt vmcnt(0)
	v_mov_b64_e32 v[16:17], 0
	v_mov_b64_e32 v[18:19], 0
	v_mov_b64_e32 v[20:21], 0
	v_mov_b64_e32 v[22:23], 0
	v_mov_b64_e32 v[32:33], 0
	v_mov_b64_e32 v[34:35], 0
	v_mov_b64_e32 v[40:41], 0
	v_mov_b64_e32 v[42:43], 0
	v_mov_b64_e32 v[48:49], 0
	v_mov_b64_e32 v[50:51], 0
	v_mov_b64_e32 v[52:53], 0
	v_mov_b64_e32 v[54:55], 0
	v_mov_b64_e32 v[56:57], 0
	v_mov_b64_e32 v[58:59], 0
	v_mov_b64_e32 v[60:61], 0
	v_mov_b64_e32 v[62:63], 0
	v_mov_b64_e32 v[64:65], 0
	v_mov_b64_e32 v[66:67], 0
	v_mov_b64_e32 v[68:69], 0
	v_mov_b64_e32 v[70:71], 0
	v_mov_b64_e32 v[72:73], 0
	v_mov_b64_e32 v[74:75], 0
	v_mov_b64_e32 v[76:77], 0
	v_mov_b64_e32 v[78:79], 0
	v_mov_b64_e32 v[80:81], 0
	v_mov_b64_e32 v[82:83], 0
	v_mov_b64_e32 v[84:85], 0
	v_mov_b64_e32 v[86:87], 0
	v_mov_b64_e32 v[88:89], 0
	v_mov_b64_e32 v[90:91], 0
	v_mov_b64_e32 v[92:93], 0
	v_mov_b64_e32 v[94:95], 0
	v_mov_b64_e32 v[96:97], 0
	v_mov_b64_e32 v[98:99], 0
	v_mov_b64_e32 v[100:101], 0
	v_mov_b64_e32 v[102:103], 0
	v_mov_b64_e32 v[104:105], 0
	v_mov_b64_e32 v[106:107], 0
	v_mov_b64_e32 v[108:109], 0
	v_mov_b64_e32 v[110:111], 0
	v_mov_b64_e32 v[112:113], 0
	v_mov_b64_e32 v[114:115], 0
	v_mov_b64_e32 v[116:117], 0
	v_mov_b64_e32 v[118:119], 0
	v_mov_b64_e32 v[120:121], 0
	v_mov_b64_e32 v[122:123], 0
	v_mov_b64_e32 v[124:125], 0
	v_mov_b64_e32 v[126:127], 0

;     __device__ bool next(int i, Unit& u) const { if (!so.next(i, u)) return false; u.ks = u.pn >= 16 ? 1 : 0; return true; }
; template <class Epi, class Order>
; __device__ __forceinline__ void gemm_phase(LAS unsigned char* lds, const Gemm g, const Order& S, const Epi& E) {
;     ...
;         const bool has_next = S.next(ui + 1, nxt);
;         const char* nA = has_next ? (const char*)g.A + (size_t)nxt.pm * tstep + (size_t)nxt.ks * sstep : cA; const char* nB = has_next ? (const char*)g.Bt + (size_t)nxt.pn * tstep + (size_t)nxt.ks * sstep : cB;
;     ...
;         if (!has_next) break;
; #pragma unroll
;         for (int a = 0; a < 2; ++a)
; #pragma unroll
;             for (int b = 0; b < 2; ++b)
; #pragma unroll
;                 for (int m = 0; m < 4; ++m)
; #pragma unroll
;                     for (int n = 0; n < 2; ++n) acc[a][b][m][n] = (f32x4){0.f, 0.f, 0.f, 0.f};
;         cur = nxt; cA = nA; cB = nB; ++ui;
.LBB0_1216:
	s_add_u32 s40, s40, 0x160080
	s_addc_u32 s41, s41, 0
	s_add_u32 s72, s42, 0x100
	v_mov_b64_e32 v[0:1], 0
	v_mov_b64_e32 v[2:3], 0
	v_mov_b64_e32 v[4:5], 0
	v_mov_b64_e32 v[6:7], 0
	v_mov_b64_e32 v[8:9], 0
	v_mov_b64_e32 v[10:11], 0
	v_mov_b64_e32 v[12:13], 0
	v_mov_b64_e32 v[14:15], 0
	v_mov_b64_e32 v[24:25], 0
	v_mov_b64_e32 v[26:27], 0
	v_mov_b64_e32 v[32:33], 0
	v_mov_b64_e32 v[34:35], 0
	v_mov_b64_e32 v[36:37], 0
	v_mov_b64_e32 v[38:39], 0
	v_mov_b64_e32 v[44:45], 0
	v_mov_b64_e32 v[46:47], 0
	s_addc_u32 s73, s43, 0
	s_mov_b32 s74, -2
	s_waitcnt vmcnt(0)
	v_mov_b64_e32 v[16:17], 0
	v_mov_b64_e32 v[18:19], 0
	v_mov_b64_e32 v[20:21], 0
	v_mov_b64_e32 v[22:23], 0
	v_mov_b64_e32 v[28:29], 0
	v_mov_b64_e32 v[30:31], 0
	v_mov_b64_e32 v[40:41], 0
	v_mov_b64_e32 v[42:43], 0
	v_mov_b64_e32 v[48:49], 0
	v_mov_b64_e32 v[50:51], 0
	v_mov_b64_e32 v[52:53], 0
	v_mov_b64_e32 v[54:55], 0
	v_mov_b64_e32 v[56:57], 0
	v_mov_b64_e32 v[58:59], 0
	v_mov_b64_e32 v[60:61], 0
	v_mov_b64_e32 v[62:63], 0
	v_mov_b64_e32 v[64:65], 0
	v_mov_b64_e32 v[66:67], 0
	v_mov_b64_e32 v[68:69], 0
	v_mov_b64_e32 v[70:71], 0
	v_mov_b64_e32 v[72:73], 0
	v_mov_b64_e32 v[74:75], 0
	v_mov_b64_e32 v[76:77], 0
	v_mov_b64_e32 v[78:79], 0
	v_mov_b64_e32 v[80:81], 0
	v_mov_b64_e32 v[82:83], 0
	v_mov_b64_e32 v[84:85], 0
	v_mov_b64_e32 v[86:87], 0
	v_mov_b64_e32 v[88:89], 0
	v_mov_b64_e32 v[90:91], 0
	v_mov_b64_e32 v[92:93], 0
	v_mov_b64_e32 v[94:95], 0
	v_mov_b64_e32 v[96:97], 0
	v_mov_b64_e32 v[98:99], 0
	v_mov_b64_e32 v[100:101], 0
	v_mov_b64_e32 v[102:103], 0
	v_mov_b64_e32 v[104:105], 0
	v_mov_b64_e32 v[106:107], 0
	v_mov_b64_e32 v[108:109], 0
	v_mov_b64_e32 v[110:111], 0
	v_mov_b64_e32 v[112:113], 0
	v_mov_b64_e32 v[114:115], 0
	v_mov_b64_e32 v[116:117], 0
	v_mov_b64_e32 v[118:119], 0
	v_mov_b64_e32 v[120:121], 0
	v_mov_b64_e32 v[122:123], 0
	v_mov_b64_e32 v[124:125], 0
	v_mov_b64_e32 v[126:127], 0
